# P8 top-16-of-128: pruned sort network (sort 16-lane rows, keep maxima of mirrored row pairs, re-sort, merge across rows) instead of the 128-wide bitonic network
# baseline (speedup 1.0000x reference)
.LBB0_922:
	s_waitcnt lgkmcnt(0)
	v_lshl_add_u64 v[2:3], v[0:1], 0, s[64:65]
	v_add_co_u32_e32 v60, vcc, 0x8008000, v2
	s_nop 1
	v_addc_co_u32_e32 v61, vcc, 0, v3, vcc
	global_load_dword v59, v[60:61], off
	global_load_dword v62, v[60:61], off offset:256
	global_load_dword v63, v[60:61], off offset:512
	s_nop 0
	global_load_dword v60, v[60:61], off offset:768
	s_waitcnt vmcnt(3)
	v_ashrrev_i32_e32 v61, 31, v59
	v_and_b32_e32 v64, 0xffffff80, v59
	s_waitcnt vmcnt(2)
	v_ashrrev_i32_e32 v65, 31, v62
	s_waitcnt vmcnt(1)
	v_ashrrev_i32_e32 v67, 31, v63
	v_and_b32_e32 v61, 0x7fffff80, v61
	v_and_b32_e32 v66, 0xffffff80, v62
	v_and_b32_e32 v68, 0xffffff80, v63
	v_and_b32_e32 v65, 0x7fffff80, v65
	v_and_b32_e32 v67, 0x7fffff80, v67
	v_bitop3_b32 v61, v61, v164, v64 bitop3:0xde
	v_bitop3_b32 v64, v65, v165, v66 bitop3:0xde
	v_bitop3_b32 v65, v67, v164, v68 bitop3:0xde
	s_waitcnt vmcnt(0)
	v_ashrrev_i32_e32 v69, 31, v60
	v_and_b32_e32 v70, 0xffffff80, v60
	v_and_b32_e32 v69, 0x7fffff80, v69
	v_bitop3_b32 v66, v69, v165, v70 bitop3:0xde
	v_mov_b32_dpp v67, v61 quad_perm:[1,0,3,2] row_mask:0xf bank_mask:0xf bound_ctrl:1
	v_mov_b32_dpp v68, v64 quad_perm:[1,0,3,2] row_mask:0xf bank_mask:0xf bound_ctrl:1
	v_mov_b32_dpp v69, v65 quad_perm:[1,0,3,2] row_mask:0xf bank_mask:0xf bound_ctrl:1
	v_mov_b32_dpp v70, v66 quad_perm:[1,0,3,2] row_mask:0xf bank_mask:0xf bound_ctrl:1
	v_med3_i32 v61, v61, v67, v100
	v_med3_i32 v64, v64, v68, v100
	v_med3_i32 v65, v65, v69, v100
	v_med3_i32 v66, v66, v70, v100
	v_mov_b32_dpp v67, v61 quad_perm:[2,3,0,1] row_mask:0xf bank_mask:0xf bound_ctrl:1
	v_mov_b32_dpp v68, v64 quad_perm:[2,3,0,1] row_mask:0xf bank_mask:0xf bound_ctrl:1
	v_mov_b32_dpp v69, v65 quad_perm:[2,3,0,1] row_mask:0xf bank_mask:0xf bound_ctrl:1
	v_mov_b32_dpp v70, v66 quad_perm:[2,3,0,1] row_mask:0xf bank_mask:0xf bound_ctrl:1
	v_med3_i32 v61, v61, v67, v101
	v_med3_i32 v64, v64, v68, v101
	v_med3_i32 v65, v65, v69, v101
	v_med3_i32 v66, v66, v70, v101
	v_mov_b32_dpp v67, v61 quad_perm:[1,0,3,2] row_mask:0xf bank_mask:0xf bound_ctrl:1
	v_mov_b32_dpp v68, v64 quad_perm:[1,0,3,2] row_mask:0xf bank_mask:0xf bound_ctrl:1
	v_mov_b32_dpp v69, v65 quad_perm:[1,0,3,2] row_mask:0xf bank_mask:0xf bound_ctrl:1
	v_mov_b32_dpp v70, v66 quad_perm:[1,0,3,2] row_mask:0xf bank_mask:0xf bound_ctrl:1
	v_med3_i32 v61, v61, v67, v102
	v_med3_i32 v64, v64, v68, v102
	v_med3_i32 v65, v65, v69, v102
	v_med3_i32 v66, v66, v70, v102
	v_mov_b32_dpp v67, v61 row_half_mirror row_mask:0xf bank_mask:0xf bound_ctrl:1
	v_mov_b32_dpp v68, v64 row_half_mirror row_mask:0xf bank_mask:0xf bound_ctrl:1
	v_mov_b32_dpp v69, v65 row_half_mirror row_mask:0xf bank_mask:0xf bound_ctrl:1
	v_mov_b32_dpp v70, v66 row_half_mirror row_mask:0xf bank_mask:0xf bound_ctrl:1
	v_mov_b32_dpp v67, v67 quad_perm:[3,2,1,0] row_mask:0xf bank_mask:0xf bound_ctrl:1
	v_mov_b32_dpp v68, v68 quad_perm:[3,2,1,0] row_mask:0xf bank_mask:0xf bound_ctrl:1
	v_mov_b32_dpp v69, v69 quad_perm:[3,2,1,0] row_mask:0xf bank_mask:0xf bound_ctrl:1
	v_mov_b32_dpp v70, v70 quad_perm:[3,2,1,0] row_mask:0xf bank_mask:0xf bound_ctrl:1
	v_med3_i32 v61, v61, v67, v103
	v_med3_i32 v64, v64, v68, v103
	v_med3_i32 v65, v65, v69, v103
	v_med3_i32 v66, v66, v70, v103
	v_mov_b32_dpp v67, v61 quad_perm:[2,3,0,1] row_mask:0xf bank_mask:0xf bound_ctrl:1
	v_mov_b32_dpp v68, v64 quad_perm:[2,3,0,1] row_mask:0xf bank_mask:0xf bound_ctrl:1
	v_mov_b32_dpp v69, v65 quad_perm:[2,3,0,1] row_mask:0xf bank_mask:0xf bound_ctrl:1
	v_mov_b32_dpp v70, v66 quad_perm:[2,3,0,1] row_mask:0xf bank_mask:0xf bound_ctrl:1
	v_med3_i32 v61, v61, v67, v104
	v_med3_i32 v64, v64, v68, v104
	v_med3_i32 v65, v65, v69, v104
	v_med3_i32 v66, v66, v70, v104
	v_mov_b32_dpp v67, v61 quad_perm:[1,0,3,2] row_mask:0xf bank_mask:0xf bound_ctrl:1
	v_mov_b32_dpp v68, v64 quad_perm:[1,0,3,2] row_mask:0xf bank_mask:0xf bound_ctrl:1
	v_mov_b32_dpp v69, v65 quad_perm:[1,0,3,2] row_mask:0xf bank_mask:0xf bound_ctrl:1
	v_mov_b32_dpp v70, v66 quad_perm:[1,0,3,2] row_mask:0xf bank_mask:0xf bound_ctrl:1
	v_med3_i32 v61, v61, v67, v105
	v_med3_i32 v64, v64, v68, v105
	v_med3_i32 v65, v65, v69, v105
	v_med3_i32 v66, v66, v70, v105
	v_mov_b32_dpp v67, v61 row_ror:8 row_mask:0xf bank_mask:0xf bound_ctrl:1
	v_mov_b32_dpp v68, v64 row_ror:8 row_mask:0xf bank_mask:0xf bound_ctrl:1
	v_mov_b32_dpp v69, v65 row_ror:8 row_mask:0xf bank_mask:0xf bound_ctrl:1
	v_mov_b32_dpp v70, v66 row_ror:8 row_mask:0xf bank_mask:0xf bound_ctrl:1
	v_med3_i32 v61, v61, v67, v119
	v_med3_i32 v64, v64, v68, v119
	v_med3_i32 v65, v65, v69, v119
	v_med3_i32 v66, v66, v70, v119
	v_mov_b32_dpp v67, v61 row_half_mirror row_mask:0xf bank_mask:0xf bound_ctrl:1
	v_mov_b32_dpp v68, v64 row_half_mirror row_mask:0xf bank_mask:0xf bound_ctrl:1
	v_mov_b32_dpp v69, v65 row_half_mirror row_mask:0xf bank_mask:0xf bound_ctrl:1
	v_mov_b32_dpp v70, v66 row_half_mirror row_mask:0xf bank_mask:0xf bound_ctrl:1
	v_mov_b32_dpp v67, v67 quad_perm:[3,2,1,0] row_mask:0xf bank_mask:0xf bound_ctrl:1
	v_mov_b32_dpp v68, v68 quad_perm:[3,2,1,0] row_mask:0xf bank_mask:0xf bound_ctrl:1
	v_mov_b32_dpp v69, v69 quad_perm:[3,2,1,0] row_mask:0xf bank_mask:0xf bound_ctrl:1
	v_mov_b32_dpp v70, v70 quad_perm:[3,2,1,0] row_mask:0xf bank_mask:0xf bound_ctrl:1
	v_med3_i32 v61, v61, v67, v121
	v_med3_i32 v64, v64, v68, v121
	v_med3_i32 v65, v65, v69, v121
	v_med3_i32 v66, v66, v70, v121
	v_mov_b32_dpp v67, v61 quad_perm:[2,3,0,1] row_mask:0xf bank_mask:0xf bound_ctrl:1
	v_mov_b32_dpp v68, v64 quad_perm:[2,3,0,1] row_mask:0xf bank_mask:0xf bound_ctrl:1
	v_mov_b32_dpp v69, v65 quad_perm:[2,3,0,1] row_mask:0xf bank_mask:0xf bound_ctrl:1
	v_mov_b32_dpp v70, v66 quad_perm:[2,3,0,1] row_mask:0xf bank_mask:0xf bound_ctrl:1
	v_med3_i32 v61, v61, v67, v123
	v_med3_i32 v64, v64, v68, v123
	v_med3_i32 v65, v65, v69, v123
	v_med3_i32 v66, v66, v70, v123
	v_mov_b32_dpp v67, v61 quad_perm:[1,0,3,2] row_mask:0xf bank_mask:0xf bound_ctrl:1
	v_mov_b32_dpp v68, v64 quad_perm:[1,0,3,2] row_mask:0xf bank_mask:0xf bound_ctrl:1
	v_mov_b32_dpp v69, v65 quad_perm:[1,0,3,2] row_mask:0xf bank_mask:0xf bound_ctrl:1
	v_mov_b32_dpp v70, v66 quad_perm:[1,0,3,2] row_mask:0xf bank_mask:0xf bound_ctrl:1
	v_med3_i32 v61, v61, v67, v125
	v_med3_i32 v64, v64, v68, v125
	v_med3_i32 v65, v65, v69, v125
	v_med3_i32 v66, v66, v70, v125
	v_max_i32_dpp v61, v64, v61 row_mirror row_mask:0xf bank_mask:0xf bound_ctrl:1
	s_nop 0
	v_max_i32_dpp v64, v66, v65 row_mirror row_mask:0xf bank_mask:0xf bound_ctrl:1
	v_mov_b32_dpp v67, v61 row_ror:8 row_mask:0xf bank_mask:0xf bound_ctrl:1
	s_nop 0
	v_mov_b32_dpp v68, v64 row_ror:8 row_mask:0xf bank_mask:0xf bound_ctrl:1
	v_med3_i32 v61, v61, v67, v106
	v_med3_i32 v64, v64, v68, v106
	s_nop 0
	v_mov_b32_dpp v67, v61 row_half_mirror row_mask:0xf bank_mask:0xf bound_ctrl:1
	v_mov_b32_dpp v68, v64 row_half_mirror row_mask:0xf bank_mask:0xf bound_ctrl:1
	s_nop 0
	v_mov_b32_dpp v67, v67 quad_perm:[3,2,1,0] row_mask:0xf bank_mask:0xf bound_ctrl:1
	v_mov_b32_dpp v68, v68 quad_perm:[3,2,1,0] row_mask:0xf bank_mask:0xf bound_ctrl:1
	v_med3_i32 v61, v61, v67, v107
	v_med3_i32 v64, v64, v68, v107
	s_nop 0
	v_mov_b32_dpp v67, v61 quad_perm:[2,3,0,1] row_mask:0xf bank_mask:0xf bound_ctrl:1
	v_mov_b32_dpp v68, v64 quad_perm:[2,3,0,1] row_mask:0xf bank_mask:0xf bound_ctrl:1
	v_med3_i32 v61, v61, v67, v108
	v_med3_i32 v64, v64, v68, v108
	s_nop 0
	v_mov_b32_dpp v67, v61 quad_perm:[1,0,3,2] row_mask:0xf bank_mask:0xf bound_ctrl:1
	v_mov_b32_dpp v68, v64 quad_perm:[1,0,3,2] row_mask:0xf bank_mask:0xf bound_ctrl:1
	v_med3_i32 v61, v61, v67, v109
	v_med3_i32 v64, v64, v68, v109
	v_mov_b32_e32 v67, v61
	v_mov_b32_e32 v68, v64
	s_nop 0
	v_permlane16_swap_b32_e32 v61, v67
	v_permlane16_swap_b32_e32 v64, v68
	v_max_i32_e32 v61, v61, v67
	v_max_i32_e32 v64, v64, v68
	s_nop 0
	v_mov_b32_dpp v67, v61 row_ror:8 row_mask:0xf bank_mask:0xf bound_ctrl:1
	v_mov_b32_dpp v68, v64 row_ror:8 row_mask:0xf bank_mask:0xf bound_ctrl:1
	v_med3_i32 v61, v61, v67, v111
	v_med3_i32 v64, v64, v68, v111
	s_nop 0
	v_mov_b32_dpp v67, v61 row_half_mirror row_mask:0xf bank_mask:0xf bound_ctrl:1
	v_mov_b32_dpp v68, v64 row_half_mirror row_mask:0xf bank_mask:0xf bound_ctrl:1
	s_nop 0
	v_mov_b32_dpp v67, v67 quad_perm:[3,2,1,0] row_mask:0xf bank_mask:0xf bound_ctrl:1
	v_mov_b32_dpp v68, v68 quad_perm:[3,2,1,0] row_mask:0xf bank_mask:0xf bound_ctrl:1
	v_med3_i32 v61, v61, v67, v112
	v_med3_i32 v64, v64, v68, v112
	s_nop 0
	v_mov_b32_dpp v67, v61 quad_perm:[2,3,0,1] row_mask:0xf bank_mask:0xf bound_ctrl:1
	v_mov_b32_dpp v68, v64 quad_perm:[2,3,0,1] row_mask:0xf bank_mask:0xf bound_ctrl:1
	v_med3_i32 v61, v61, v67, v113
	v_med3_i32 v64, v64, v68, v113
	s_nop 0
	v_mov_b32_dpp v67, v61 quad_perm:[1,0,3,2] row_mask:0xf bank_mask:0xf bound_ctrl:1
	v_mov_b32_dpp v68, v64 quad_perm:[1,0,3,2] row_mask:0xf bank_mask:0xf bound_ctrl:1
	v_med3_i32 v61, v61, v67, v114
	v_med3_i32 v64, v64, v68, v114
	v_mov_b32_e32 v67, v61
	v_mov_b32_e32 v68, v64
	s_nop 0
	v_permlane32_swap_b32_e32 v61, v67
	v_permlane32_swap_b32_e32 v64, v68
	v_max_i32_e32 v61, v61, v67
	v_max_i32_e32 v64, v64, v68
	s_nop 0
	v_mov_b32_dpp v67, v61 row_ror:8 row_mask:0xf bank_mask:0xf bound_ctrl:1
	v_mov_b32_dpp v68, v64 row_ror:8 row_mask:0xf bank_mask:0xf bound_ctrl:1
	v_med3_i32 v61, v61, v67, v119
	v_med3_i32 v64, v64, v68, v119
	s_nop 0
	v_mov_b32_dpp v67, v61 row_half_mirror row_mask:0xf bank_mask:0xf bound_ctrl:1
	v_mov_b32_dpp v68, v64 row_half_mirror row_mask:0xf bank_mask:0xf bound_ctrl:1
	s_nop 0
	v_mov_b32_dpp v67, v67 quad_perm:[3,2,1,0] row_mask:0xf bank_mask:0xf bound_ctrl:1
	v_mov_b32_dpp v68, v68 quad_perm:[3,2,1,0] row_mask:0xf bank_mask:0xf bound_ctrl:1
	v_med3_i32 v61, v61, v67, v121
	v_med3_i32 v64, v64, v68, v121
	s_nop 0
	v_mov_b32_dpp v67, v61 quad_perm:[2,3,0,1] row_mask:0xf bank_mask:0xf bound_ctrl:1
	v_mov_b32_dpp v68, v64 quad_perm:[2,3,0,1] row_mask:0xf bank_mask:0xf bound_ctrl:1
	v_med3_i32 v61, v61, v67, v123
	v_med3_i32 v64, v64, v68, v123
	s_nop 0
	v_mov_b32_dpp v67, v61 quad_perm:[1,0,3,2] row_mask:0xf bank_mask:0xf bound_ctrl:1
	v_mov_b32_dpp v68, v64 quad_perm:[1,0,3,2] row_mask:0xf bank_mask:0xf bound_ctrl:1
	v_med3_i32 v61, v61, v67, v125
	v_med3_i32 v64, v64, v68, v125
	v_bitop3_b32 v65, v61, s78, v61 bitop3:0xc
	v_bitop3_b32 v61, v61, v166, 63 bitop3:0xce
	v_lshlrev_b32_e32 v61, 2, v61
	ds_bpermute_b32 v59, v61, v59
	ds_bpermute_b32 v61, v61, v62
	v_bitop3_b32 v62, v64, v166, 63 bitop3:0xce
	v_lshlrev_b32_e32 v62, 2, v62
	ds_bpermute_b32 v63, v62, v63
	ds_bpermute_b32 v60, v62, v60
	v_bitop3_b32 v62, v64, s78, v64 bitop3:0xc
	v_cmp_gt_u32_e32 vcc, 64, v65
	s_waitcnt lgkmcnt(2)
	s_nop 0
	v_cndmask_b32_e32 v59, v61, v59, vcc
	v_cmp_gt_u32_e32 vcc, 64, v62
	ds_bpermute_b32 v59, v167, v59
	ds_bpermute_b32 v62, v168, v62
	s_waitcnt lgkmcnt(2)
	v_cndmask_b32_e32 v60, v60, v63, vcc
	ds_bpermute_b32 v60, v168, v60
	s_waitcnt lgkmcnt(0)
	v_add_f32_e32 v59, v59, v60
	v_ashrrev_i32_e32 v60, 31, v59
	v_and_b32_e32 v60, 0x7fffffc0, v60
	v_and_b32_e32 v61, 0xffffffc0, v59
	v_bitop3_b32 v60, v60, v165, v61 bitop3:0xde
	v_cndmask_b32_e64 v60, v60, v173, s[4:5]
	s_nop 1
	v_mov_b32_dpp v61, v60 quad_perm:[1,0,3,2] row_mask:0xf bank_mask:0xf bound_ctrl:1
	v_med3_i32 v60, v60, v61, v100
	s_nop 1
	v_mov_b32_dpp v61, v60 quad_perm:[2,3,0,1] row_mask:0xf bank_mask:0xf bound_ctrl:1
	v_med3_i32 v60, v60, v61, v101
	s_nop 1
	v_mov_b32_dpp v61, v60 quad_perm:[1,0,3,2] row_mask:0xf bank_mask:0xf bound_ctrl:1
	v_med3_i32 v60, v60, v61, v102
	s_nop 1
	v_mov_b32_dpp v61, v60 row_half_mirror row_mask:0xf bank_mask:0xf bound_ctrl:1
	s_nop 1
	v_mov_b32_dpp v63, v61 quad_perm:[3,2,1,0] row_mask:0xf bank_mask:0xf bound_ctrl:1
	v_med3_i32 v60, v60, v63, v103
	s_nop 1
	v_mov_b32_dpp v61, v60 quad_perm:[2,3,0,1] row_mask:0xf bank_mask:0xf bound_ctrl:1
	v_med3_i32 v60, v60, v61, v104
	s_nop 1
	v_mov_b32_dpp v61, v60 quad_perm:[1,0,3,2] row_mask:0xf bank_mask:0xf bound_ctrl:1
	v_med3_i32 v60, v60, v61, v105
	s_nop 1
	v_mov_b32_dpp v61, v60 row_ror:8 row_mask:0xf bank_mask:0xf bound_ctrl:1
	v_med3_i32 v60, v60, v61, v106
	s_nop 1
	v_mov_b32_dpp v61, v60 row_half_mirror row_mask:0xf bank_mask:0xf bound_ctrl:1
	s_nop 1
	v_mov_b32_dpp v63, v61 quad_perm:[3,2,1,0] row_mask:0xf bank_mask:0xf bound_ctrl:1
	v_med3_i32 v60, v60, v63, v107
	s_nop 1
	v_mov_b32_dpp v61, v60 quad_perm:[2,3,0,1] row_mask:0xf bank_mask:0xf bound_ctrl:1
	v_med3_i32 v60, v60, v61, v108
	s_nop 1
	v_mov_b32_dpp v61, v60 quad_perm:[1,0,3,2] row_mask:0xf bank_mask:0xf bound_ctrl:1
	v_med3_i32 v60, v60, v61, v109
	v_mov_b32_e32 v63, v60
	s_nop 1
	v_permlane16_swap_b32_e32 v60, v63
	v_med3_i32 v60, v60, v63, v110
	s_nop 1
	v_mov_b32_dpp v61, v60 row_ror:8 row_mask:0xf bank_mask:0xf bound_ctrl:1
	v_med3_i32 v60, v60, v61, v111
	s_nop 1
	v_mov_b32_dpp v61, v60 row_half_mirror row_mask:0xf bank_mask:0xf bound_ctrl:1
	s_nop 1
	v_mov_b32_dpp v63, v61 quad_perm:[3,2,1,0] row_mask:0xf bank_mask:0xf bound_ctrl:1
	v_med3_i32 v60, v60, v63, v112
	s_nop 1
	v_mov_b32_dpp v61, v60 quad_perm:[2,3,0,1] row_mask:0xf bank_mask:0xf bound_ctrl:1
	v_med3_i32 v60, v60, v61, v113
	s_nop 1
	v_mov_b32_dpp v61, v60 quad_perm:[1,0,3,2] row_mask:0xf bank_mask:0xf bound_ctrl:1
	v_med3_i32 v60, v60, v61, v114
	v_mov_b32_e32 v63, v60
	s_nop 1
	v_permlane32_swap_b32_e32 v60, v63
	v_med3_i32 v60, v60, v63, v127
	v_mov_b32_e32 v63, v60
	s_nop 1
	v_permlane16_swap_b32_e32 v60, v63
	v_med3_i32 v60, v60, v63, v117
	s_nop 1
	v_mov_b32_dpp v61, v60 row_ror:8 row_mask:0xf bank_mask:0xf bound_ctrl:1
	v_med3_i32 v60, v60, v61, v119
	s_nop 1
	v_mov_b32_dpp v61, v60 row_half_mirror row_mask:0xf bank_mask:0xf bound_ctrl:1
	s_nop 1
	v_mov_b32_dpp v63, v61 quad_perm:[3,2,1,0] row_mask:0xf bank_mask:0xf bound_ctrl:1
	v_med3_i32 v60, v60, v63, v121
	s_nop 1
	v_mov_b32_dpp v61, v60 quad_perm:[2,3,0,1] row_mask:0xf bank_mask:0xf bound_ctrl:1
	v_med3_i32 v60, v60, v61, v123
	s_nop 1
	v_mov_b32_dpp v61, v60 quad_perm:[1,0,3,2] row_mask:0xf bank_mask:0xf bound_ctrl:1
	v_med3_i32 v60, v60, v61, v125
	v_and_or_b32 v60, v60, 63, v166
	v_lshlrev_b32_e32 v60, 2, v60
	v_xor_b32_e32 v60, 0xfc, v60
	ds_bpermute_b32 v59, v60, v59
	ds_bpermute_b32 v61, v167, v65
	s_waitcnt lgkmcnt(1)
	v_readlane_b32 s33, v59, 0
	s_nop 1
	v_subrev_f32_e32 v59, s33, v59
	v_mul_f32_e32 v59, v24, v59
	v_mul_f32_e32 v59, 0x3fb8aa3b, v59
	v_exp_f32_e32 v59, v59
	s_waitcnt lgkmcnt(0)
	v_lshl_add_u32 v61, v61, 7, v62
	ds_bpermute_b32 v60, v60, v61
	v_cndmask_b32_e64 v61, 0, v59, s[54:55]
	s_nop 1
	v_add_f32_dpp v61, v61, v61 row_ror:8 row_mask:0xf bank_mask:0xf bound_ctrl:1
	s_nop 1
	v_mov_b32_dpp v62, v61 row_half_mirror row_mask:0xf bank_mask:0xf bound_ctrl:1
	s_nop 1
	v_add_f32_dpp v61, v62, v61 quad_perm:[3,2,1,0] row_mask:0xf bank_mask:0xf bound_ctrl:1
	s_nop 1
	v_add_f32_dpp v61, v61, v61 quad_perm:[2,3,0,1] row_mask:0xf bank_mask:0xf bound_ctrl:1
	s_nop 1
	v_mov_b32_dpp v62, v61 quad_perm:[1,0,3,2] row_mask:0xf bank_mask:0xf bound_ctrl:1
	s_and_saveexec_b64 s[66:67], s[54:55]
	s_cbranch_execz .LBB0_924
	v_add_f32_e32 v61, v61, v62
	v_div_scale_f32 v62, s[68:69], v61, v61, v59
	v_rcp_f32_e32 v63, v62
	v_div_scale_f32 v64, vcc, v59, v61, v59
	v_fma_f32 v65, -v62, v63, 1.0
	v_fmac_f32_e32 v63, v65, v63
	v_mul_f32_e32 v65, v64, v63
	v_fma_f32 v66, -v62, v65, v64
	v_fmac_f32_e32 v65, v66, v63
	v_fma_f32 v62, -v62, v65, v64
	v_div_fmas_f32 v62, v62, v63, v65
	v_div_fixup_f32 v59, v62, v61, v59
	s_waitcnt lgkmcnt(0)
	ds_write2st64_b32 v28, v60, v59 offset1:2
.LBB0_924:
	s_or_b64 exec, exec, s[66:67]
	v_add_co_u32_e32 v2, vcc, 0x8008000, v2
	s_nop 1
	v_addc_co_u32_e32 v3, vcc, 0, v3, vcc
	global_load_dword v59, v[2:3], off offset:1024
	s_waitcnt lgkmcnt(0)
	global_load_dword v60, v[2:3], off offset:1280
	global_load_dword v61, v[2:3], off offset:1536
	s_nop 0
	global_load_dword v2, v[2:3], off offset:1792
	s_waitcnt vmcnt(3)
	v_ashrrev_i32_e32 v3, 31, v59
	v_and_b32_e32 v62, 0xffffff80, v59
	s_waitcnt vmcnt(2)
	v_ashrrev_i32_e32 v63, 31, v60
	s_waitcnt vmcnt(1)
	v_ashrrev_i32_e32 v65, 31, v61
	v_and_b32_e32 v3, 0x7fffff80, v3
	v_and_b32_e32 v64, 0xffffff80, v60
	v_and_b32_e32 v66, 0xffffff80, v61
	v_and_b32_e32 v63, 0x7fffff80, v63
	v_and_b32_e32 v65, 0x7fffff80, v65
	v_bitop3_b32 v3, v3, v164, v62 bitop3:0xde
	v_bitop3_b32 v62, v63, v165, v64 bitop3:0xde
	v_bitop3_b32 v63, v65, v164, v66 bitop3:0xde
	s_waitcnt vmcnt(0)
	v_ashrrev_i32_e32 v67, 31, v2
	v_and_b32_e32 v68, 0xffffff80, v2
	v_and_b32_e32 v67, 0x7fffff80, v67
	v_bitop3_b32 v64, v67, v165, v68 bitop3:0xde
	v_mov_b32_dpp v65, v3 quad_perm:[1,0,3,2] row_mask:0xf bank_mask:0xf bound_ctrl:1
	v_mov_b32_dpp v66, v62 quad_perm:[1,0,3,2] row_mask:0xf bank_mask:0xf bound_ctrl:1
	v_mov_b32_dpp v67, v63 quad_perm:[1,0,3,2] row_mask:0xf bank_mask:0xf bound_ctrl:1
	v_mov_b32_dpp v68, v64 quad_perm:[1,0,3,2] row_mask:0xf bank_mask:0xf bound_ctrl:1
	v_med3_i32 v3, v3, v65, v100
	v_med3_i32 v62, v62, v66, v100
	v_med3_i32 v63, v63, v67, v100
	v_med3_i32 v64, v64, v68, v100
	v_mov_b32_dpp v65, v3 quad_perm:[2,3,0,1] row_mask:0xf bank_mask:0xf bound_ctrl:1
	v_mov_b32_dpp v66, v62 quad_perm:[2,3,0,1] row_mask:0xf bank_mask:0xf bound_ctrl:1
	v_mov_b32_dpp v67, v63 quad_perm:[2,3,0,1] row_mask:0xf bank_mask:0xf bound_ctrl:1
	v_mov_b32_dpp v68, v64 quad_perm:[2,3,0,1] row_mask:0xf bank_mask:0xf bound_ctrl:1
	v_med3_i32 v3, v3, v65, v101
	v_med3_i32 v62, v62, v66, v101
	v_med3_i32 v63, v63, v67, v101
	v_med3_i32 v64, v64, v68, v101
	v_mov_b32_dpp v65, v3 quad_perm:[1,0,3,2] row_mask:0xf bank_mask:0xf bound_ctrl:1
	v_mov_b32_dpp v66, v62 quad_perm:[1,0,3,2] row_mask:0xf bank_mask:0xf bound_ctrl:1
	v_mov_b32_dpp v67, v63 quad_perm:[1,0,3,2] row_mask:0xf bank_mask:0xf bound_ctrl:1
	v_mov_b32_dpp v68, v64 quad_perm:[1,0,3,2] row_mask:0xf bank_mask:0xf bound_ctrl:1
	v_med3_i32 v3, v3, v65, v102
	v_med3_i32 v62, v62, v66, v102
	v_med3_i32 v63, v63, v67, v102
	v_med3_i32 v64, v64, v68, v102
	v_mov_b32_dpp v65, v3 row_half_mirror row_mask:0xf bank_mask:0xf bound_ctrl:1
	v_mov_b32_dpp v66, v62 row_half_mirror row_mask:0xf bank_mask:0xf bound_ctrl:1
	v_mov_b32_dpp v67, v63 row_half_mirror row_mask:0xf bank_mask:0xf bound_ctrl:1
	v_mov_b32_dpp v68, v64 row_half_mirror row_mask:0xf bank_mask:0xf bound_ctrl:1
	v_mov_b32_dpp v65, v65 quad_perm:[3,2,1,0] row_mask:0xf bank_mask:0xf bound_ctrl:1
	v_mov_b32_dpp v66, v66 quad_perm:[3,2,1,0] row_mask:0xf bank_mask:0xf bound_ctrl:1
	v_mov_b32_dpp v67, v67 quad_perm:[3,2,1,0] row_mask:0xf bank_mask:0xf bound_ctrl:1
	v_mov_b32_dpp v68, v68 quad_perm:[3,2,1,0] row_mask:0xf bank_mask:0xf bound_ctrl:1
	v_med3_i32 v3, v3, v65, v103
	v_med3_i32 v62, v62, v66, v103
	v_med3_i32 v63, v63, v67, v103
	v_med3_i32 v64, v64, v68, v103
	v_mov_b32_dpp v65, v3 quad_perm:[2,3,0,1] row_mask:0xf bank_mask:0xf bound_ctrl:1
	v_mov_b32_dpp v66, v62 quad_perm:[2,3,0,1] row_mask:0xf bank_mask:0xf bound_ctrl:1
	v_mov_b32_dpp v67, v63 quad_perm:[2,3,0,1] row_mask:0xf bank_mask:0xf bound_ctrl:1
	v_mov_b32_dpp v68, v64 quad_perm:[2,3,0,1] row_mask:0xf bank_mask:0xf bound_ctrl:1
	v_med3_i32 v3, v3, v65, v104
	v_med3_i32 v62, v62, v66, v104
	v_med3_i32 v63, v63, v67, v104
	v_med3_i32 v64, v64, v68, v104
	v_mov_b32_dpp v65, v3 quad_perm:[1,0,3,2] row_mask:0xf bank_mask:0xf bound_ctrl:1
	v_mov_b32_dpp v66, v62 quad_perm:[1,0,3,2] row_mask:0xf bank_mask:0xf bound_ctrl:1
	v_mov_b32_dpp v67, v63 quad_perm:[1,0,3,2] row_mask:0xf bank_mask:0xf bound_ctrl:1
	v_mov_b32_dpp v68, v64 quad_perm:[1,0,3,2] row_mask:0xf bank_mask:0xf bound_ctrl:1
	v_med3_i32 v3, v3, v65, v105
	v_med3_i32 v62, v62, v66, v105
	v_med3_i32 v63, v63, v67, v105
	v_med3_i32 v64, v64, v68, v105
	v_mov_b32_dpp v65, v3 row_ror:8 row_mask:0xf bank_mask:0xf bound_ctrl:1
	v_mov_b32_dpp v66, v62 row_ror:8 row_mask:0xf bank_mask:0xf bound_ctrl:1
	v_mov_b32_dpp v67, v63 row_ror:8 row_mask:0xf bank_mask:0xf bound_ctrl:1
	v_mov_b32_dpp v68, v64 row_ror:8 row_mask:0xf bank_mask:0xf bound_ctrl:1
	v_med3_i32 v3, v3, v65, v119
	v_med3_i32 v62, v62, v66, v119
	v_med3_i32 v63, v63, v67, v119
	v_med3_i32 v64, v64, v68, v119
	v_mov_b32_dpp v65, v3 row_half_mirror row_mask:0xf bank_mask:0xf bound_ctrl:1
	v_mov_b32_dpp v66, v62 row_half_mirror row_mask:0xf bank_mask:0xf bound_ctrl:1
	v_mov_b32_dpp v67, v63 row_half_mirror row_mask:0xf bank_mask:0xf bound_ctrl:1
	v_mov_b32_dpp v68, v64 row_half_mirror row_mask:0xf bank_mask:0xf bound_ctrl:1
	v_mov_b32_dpp v65, v65 quad_perm:[3,2,1,0] row_mask:0xf bank_mask:0xf bound_ctrl:1
	v_mov_b32_dpp v66, v66 quad_perm:[3,2,1,0] row_mask:0xf bank_mask:0xf bound_ctrl:1
	v_mov_b32_dpp v67, v67 quad_perm:[3,2,1,0] row_mask:0xf bank_mask:0xf bound_ctrl:1
	v_mov_b32_dpp v68, v68 quad_perm:[3,2,1,0] row_mask:0xf bank_mask:0xf bound_ctrl:1
	v_med3_i32 v3, v3, v65, v121
	v_med3_i32 v62, v62, v66, v121
	v_med3_i32 v63, v63, v67, v121
	v_med3_i32 v64, v64, v68, v121
	v_mov_b32_dpp v65, v3 quad_perm:[2,3,0,1] row_mask:0xf bank_mask:0xf bound_ctrl:1
	v_mov_b32_dpp v66, v62 quad_perm:[2,3,0,1] row_mask:0xf bank_mask:0xf bound_ctrl:1
	v_mov_b32_dpp v67, v63 quad_perm:[2,3,0,1] row_mask:0xf bank_mask:0xf bound_ctrl:1
	v_mov_b32_dpp v68, v64 quad_perm:[2,3,0,1] row_mask:0xf bank_mask:0xf bound_ctrl:1
	v_med3_i32 v3, v3, v65, v123
	v_med3_i32 v62, v62, v66, v123
	v_med3_i32 v63, v63, v67, v123
	v_med3_i32 v64, v64, v68, v123
	v_mov_b32_dpp v65, v3 quad_perm:[1,0,3,2] row_mask:0xf bank_mask:0xf bound_ctrl:1
	v_mov_b32_dpp v66, v62 quad_perm:[1,0,3,2] row_mask:0xf bank_mask:0xf bound_ctrl:1
	v_mov_b32_dpp v67, v63 quad_perm:[1,0,3,2] row_mask:0xf bank_mask:0xf bound_ctrl:1
	v_mov_b32_dpp v68, v64 quad_perm:[1,0,3,2] row_mask:0xf bank_mask:0xf bound_ctrl:1
	v_med3_i32 v3, v3, v65, v125
	v_med3_i32 v62, v62, v66, v125
	v_med3_i32 v63, v63, v67, v125
	v_med3_i32 v64, v64, v68, v125
	v_max_i32_dpp v3, v62, v3 row_mirror row_mask:0xf bank_mask:0xf bound_ctrl:1
	s_nop 0
	v_max_i32_dpp v62, v64, v63 row_mirror row_mask:0xf bank_mask:0xf bound_ctrl:1
	v_mov_b32_dpp v65, v3 row_ror:8 row_mask:0xf bank_mask:0xf bound_ctrl:1
	s_nop 0
	v_mov_b32_dpp v66, v62 row_ror:8 row_mask:0xf bank_mask:0xf bound_ctrl:1
	v_med3_i32 v3, v3, v65, v106
	v_med3_i32 v62, v62, v66, v106
	s_nop 0
	v_mov_b32_dpp v65, v3 row_half_mirror row_mask:0xf bank_mask:0xf bound_ctrl:1
	v_mov_b32_dpp v66, v62 row_half_mirror row_mask:0xf bank_mask:0xf bound_ctrl:1
	s_nop 0
	v_mov_b32_dpp v65, v65 quad_perm:[3,2,1,0] row_mask:0xf bank_mask:0xf bound_ctrl:1
	v_mov_b32_dpp v66, v66 quad_perm:[3,2,1,0] row_mask:0xf bank_mask:0xf bound_ctrl:1
	v_med3_i32 v3, v3, v65, v107
	v_med3_i32 v62, v62, v66, v107
	s_nop 0
	v_mov_b32_dpp v65, v3 quad_perm:[2,3,0,1] row_mask:0xf bank_mask:0xf bound_ctrl:1
	v_mov_b32_dpp v66, v62 quad_perm:[2,3,0,1] row_mask:0xf bank_mask:0xf bound_ctrl:1
	v_med3_i32 v3, v3, v65, v108
	v_med3_i32 v62, v62, v66, v108
	s_nop 0
	v_mov_b32_dpp v65, v3 quad_perm:[1,0,3,2] row_mask:0xf bank_mask:0xf bound_ctrl:1
	v_mov_b32_dpp v66, v62 quad_perm:[1,0,3,2] row_mask:0xf bank_mask:0xf bound_ctrl:1
	v_med3_i32 v3, v3, v65, v109
	v_med3_i32 v62, v62, v66, v109
	v_mov_b32_e32 v65, v3
	v_mov_b32_e32 v66, v62
	s_nop 0
	v_permlane16_swap_b32_e32 v3, v65
	v_permlane16_swap_b32_e32 v62, v66
	v_max_i32_e32 v3, v3, v65
	v_max_i32_e32 v62, v62, v66
	s_nop 0
	v_mov_b32_dpp v65, v3 row_ror:8 row_mask:0xf bank_mask:0xf bound_ctrl:1
	v_mov_b32_dpp v66, v62 row_ror:8 row_mask:0xf bank_mask:0xf bound_ctrl:1
	v_med3_i32 v3, v3, v65, v111
	v_med3_i32 v62, v62, v66, v111
	s_nop 0
	v_mov_b32_dpp v65, v3 row_half_mirror row_mask:0xf bank_mask:0xf bound_ctrl:1
	v_mov_b32_dpp v66, v62 row_half_mirror row_mask:0xf bank_mask:0xf bound_ctrl:1
	s_nop 0
	v_mov_b32_dpp v65, v65 quad_perm:[3,2,1,0] row_mask:0xf bank_mask:0xf bound_ctrl:1
	v_mov_b32_dpp v66, v66 quad_perm:[3,2,1,0] row_mask:0xf bank_mask:0xf bound_ctrl:1
	v_med3_i32 v3, v3, v65, v112
	v_med3_i32 v62, v62, v66, v112
	s_nop 0
	v_mov_b32_dpp v65, v3 quad_perm:[2,3,0,1] row_mask:0xf bank_mask:0xf bound_ctrl:1
	v_mov_b32_dpp v66, v62 quad_perm:[2,3,0,1] row_mask:0xf bank_mask:0xf bound_ctrl:1
	v_med3_i32 v3, v3, v65, v113
	v_med3_i32 v62, v62, v66, v113
	s_nop 0
	v_mov_b32_dpp v65, v3 quad_perm:[1,0,3,2] row_mask:0xf bank_mask:0xf bound_ctrl:1
	v_mov_b32_dpp v66, v62 quad_perm:[1,0,3,2] row_mask:0xf bank_mask:0xf bound_ctrl:1
	v_med3_i32 v3, v3, v65, v114
	v_med3_i32 v62, v62, v66, v114
	v_mov_b32_e32 v65, v3
	v_mov_b32_e32 v66, v62
	s_nop 0
	v_permlane32_swap_b32_e32 v3, v65
	v_permlane32_swap_b32_e32 v62, v66
	v_max_i32_e32 v3, v3, v65
	v_max_i32_e32 v62, v62, v66
	s_nop 0
	v_mov_b32_dpp v65, v3 row_ror:8 row_mask:0xf bank_mask:0xf bound_ctrl:1
	v_mov_b32_dpp v66, v62 row_ror:8 row_mask:0xf bank_mask:0xf bound_ctrl:1
	v_med3_i32 v3, v3, v65, v119
	v_med3_i32 v62, v62, v66, v119
	s_nop 0
	v_mov_b32_dpp v65, v3 row_half_mirror row_mask:0xf bank_mask:0xf bound_ctrl:1
	v_mov_b32_dpp v66, v62 row_half_mirror row_mask:0xf bank_mask:0xf bound_ctrl:1
	s_nop 0
	v_mov_b32_dpp v65, v65 quad_perm:[3,2,1,0] row_mask:0xf bank_mask:0xf bound_ctrl:1
	v_mov_b32_dpp v66, v66 quad_perm:[3,2,1,0] row_mask:0xf bank_mask:0xf bound_ctrl:1
	v_med3_i32 v3, v3, v65, v121
	v_med3_i32 v62, v62, v66, v121
	s_nop 0
	v_mov_b32_dpp v65, v3 quad_perm:[2,3,0,1] row_mask:0xf bank_mask:0xf bound_ctrl:1
	v_mov_b32_dpp v66, v62 quad_perm:[2,3,0,1] row_mask:0xf bank_mask:0xf bound_ctrl:1
	v_med3_i32 v3, v3, v65, v123
	v_med3_i32 v62, v62, v66, v123
	s_nop 0
	v_mov_b32_dpp v65, v3 quad_perm:[1,0,3,2] row_mask:0xf bank_mask:0xf bound_ctrl:1
	v_mov_b32_dpp v66, v62 quad_perm:[1,0,3,2] row_mask:0xf bank_mask:0xf bound_ctrl:1
	v_med3_i32 v3, v3, v65, v125
	v_med3_i32 v62, v62, v66, v125
	v_bitop3_b32 v63, v3, s78, v3 bitop3:0xc
	v_bitop3_b32 v3, v3, v166, 63 bitop3:0xce
	v_lshlrev_b32_e32 v3, 2, v3
	ds_bpermute_b32 v59, v3, v59
	ds_bpermute_b32 v3, v3, v60
	v_bitop3_b32 v60, v62, v166, 63 bitop3:0xce
	v_lshlrev_b32_e32 v60, 2, v60
	ds_bpermute_b32 v61, v60, v61
	ds_bpermute_b32 v2, v60, v2
	v_bitop3_b32 v60, v62, s78, v62 bitop3:0xc
	v_cmp_gt_u32_e32 vcc, 64, v63
	s_waitcnt lgkmcnt(2)
	s_nop 0
	v_cndmask_b32_e32 v3, v3, v59, vcc
	v_cmp_gt_u32_e32 vcc, 64, v60
	ds_bpermute_b32 v3, v167, v3
	ds_bpermute_b32 v60, v168, v60
	s_waitcnt lgkmcnt(2)
	v_cndmask_b32_e32 v2, v2, v61, vcc
	ds_bpermute_b32 v2, v168, v2
	s_waitcnt lgkmcnt(0)
	v_add_f32_e32 v2, v3, v2
	v_ashrrev_i32_e32 v3, 31, v2
	v_and_b32_e32 v3, 0x7fffffc0, v3
	v_and_b32_e32 v59, 0xffffffc0, v2
	v_bitop3_b32 v3, v3, v165, v59 bitop3:0xde
	v_cndmask_b32_e64 v3, v3, v173, s[4:5]
	s_nop 1
	v_mov_b32_dpp v59, v3 quad_perm:[1,0,3,2] row_mask:0xf bank_mask:0xf bound_ctrl:1
	v_med3_i32 v3, v3, v59, v100
	s_nop 1
	v_mov_b32_dpp v59, v3 quad_perm:[2,3,0,1] row_mask:0xf bank_mask:0xf bound_ctrl:1
	v_med3_i32 v3, v3, v59, v101
	s_nop 1
	v_mov_b32_dpp v59, v3 quad_perm:[1,0,3,2] row_mask:0xf bank_mask:0xf bound_ctrl:1
	v_med3_i32 v3, v3, v59, v102
	s_nop 1
	v_mov_b32_dpp v59, v3 row_half_mirror row_mask:0xf bank_mask:0xf bound_ctrl:1
	s_nop 1
	v_mov_b32_dpp v61, v59 quad_perm:[3,2,1,0] row_mask:0xf bank_mask:0xf bound_ctrl:1
	v_med3_i32 v3, v3, v61, v103
	s_nop 1
	v_mov_b32_dpp v59, v3 quad_perm:[2,3,0,1] row_mask:0xf bank_mask:0xf bound_ctrl:1
	v_med3_i32 v3, v3, v59, v104
	s_nop 1
	v_mov_b32_dpp v59, v3 quad_perm:[1,0,3,2] row_mask:0xf bank_mask:0xf bound_ctrl:1
	v_med3_i32 v3, v3, v59, v105
	s_nop 1
	v_mov_b32_dpp v59, v3 row_ror:8 row_mask:0xf bank_mask:0xf bound_ctrl:1
	v_med3_i32 v3, v3, v59, v106
	s_nop 1
	v_mov_b32_dpp v59, v3 row_half_mirror row_mask:0xf bank_mask:0xf bound_ctrl:1
	s_nop 1
	v_mov_b32_dpp v61, v59 quad_perm:[3,2,1,0] row_mask:0xf bank_mask:0xf bound_ctrl:1
	v_med3_i32 v3, v3, v61, v107
	s_nop 1
	v_mov_b32_dpp v59, v3 quad_perm:[2,3,0,1] row_mask:0xf bank_mask:0xf bound_ctrl:1
	v_med3_i32 v3, v3, v59, v108
	s_nop 1
	v_mov_b32_dpp v59, v3 quad_perm:[1,0,3,2] row_mask:0xf bank_mask:0xf bound_ctrl:1
	v_med3_i32 v3, v3, v59, v109
	v_mov_b32_e32 v61, v3
	s_nop 1
	v_permlane16_swap_b32_e32 v3, v61
	v_med3_i32 v3, v3, v61, v110
	s_nop 1
	v_mov_b32_dpp v59, v3 row_ror:8 row_mask:0xf bank_mask:0xf bound_ctrl:1
	v_med3_i32 v3, v3, v59, v111
	s_nop 1
	v_mov_b32_dpp v59, v3 row_half_mirror row_mask:0xf bank_mask:0xf bound_ctrl:1
	s_nop 1
	v_mov_b32_dpp v61, v59 quad_perm:[3,2,1,0] row_mask:0xf bank_mask:0xf bound_ctrl:1
	v_med3_i32 v3, v3, v61, v112
	s_nop 1
	v_mov_b32_dpp v59, v3 quad_perm:[2,3,0,1] row_mask:0xf bank_mask:0xf bound_ctrl:1
	v_med3_i32 v3, v3, v59, v113
	s_nop 1
	v_mov_b32_dpp v59, v3 quad_perm:[1,0,3,2] row_mask:0xf bank_mask:0xf bound_ctrl:1
	v_med3_i32 v3, v3, v59, v114
	v_mov_b32_e32 v61, v3
	s_nop 1
	v_permlane32_swap_b32_e32 v3, v61
	v_med3_i32 v3, v3, v61, v127
	v_mov_b32_e32 v61, v3
	s_nop 1
	v_permlane16_swap_b32_e32 v3, v61
	v_med3_i32 v3, v3, v61, v117
	s_nop 1
	v_mov_b32_dpp v59, v3 row_ror:8 row_mask:0xf bank_mask:0xf bound_ctrl:1
	v_med3_i32 v3, v3, v59, v119
	s_nop 1
	v_mov_b32_dpp v59, v3 row_half_mirror row_mask:0xf bank_mask:0xf bound_ctrl:1
	s_nop 1
	v_mov_b32_dpp v61, v59 quad_perm:[3,2,1,0] row_mask:0xf bank_mask:0xf bound_ctrl:1
	v_med3_i32 v3, v3, v61, v121
	s_nop 1
	v_mov_b32_dpp v59, v3 quad_perm:[2,3,0,1] row_mask:0xf bank_mask:0xf bound_ctrl:1
	v_med3_i32 v3, v3, v59, v123
	s_nop 1
	v_mov_b32_dpp v59, v3 quad_perm:[1,0,3,2] row_mask:0xf bank_mask:0xf bound_ctrl:1
	v_med3_i32 v3, v3, v59, v125
	v_and_or_b32 v3, v3, 63, v166
	v_lshlrev_b32_e32 v3, 2, v3
	v_xor_b32_e32 v3, 0xfc, v3
	ds_bpermute_b32 v2, v3, v2
	ds_bpermute_b32 v59, v167, v63
	s_waitcnt lgkmcnt(1)
	v_readlane_b32 s33, v2, 0
	s_nop 1
	v_subrev_f32_e32 v2, s33, v2
	v_mul_f32_e32 v2, v24, v2
	v_mul_f32_e32 v2, 0x3fb8aa3b, v2
	v_exp_f32_e32 v2, v2
	s_waitcnt lgkmcnt(0)
	v_lshl_add_u32 v59, v59, 7, v60
	ds_bpermute_b32 v3, v3, v59
	v_cndmask_b32_e64 v59, 0, v2, s[54:55]
	s_nop 1
	v_add_f32_dpp v59, v59, v59 row_ror:8 row_mask:0xf bank_mask:0xf bound_ctrl:1
	s_nop 1
	v_mov_b32_dpp v60, v59 row_half_mirror row_mask:0xf bank_mask:0xf bound_ctrl:1
	s_nop 1
	v_add_f32_dpp v59, v60, v59 quad_perm:[3,2,1,0] row_mask:0xf bank_mask:0xf bound_ctrl:1
	s_nop 1
	v_add_f32_dpp v59, v59, v59 quad_perm:[2,3,0,1] row_mask:0xf bank_mask:0xf bound_ctrl:1
	s_nop 1
	v_mov_b32_dpp v60, v59 quad_perm:[1,0,3,2] row_mask:0xf bank_mask:0xf bound_ctrl:1
	s_and_saveexec_b64 s[66:67], s[54:55]
	s_cbranch_execz .LBB0_921
	v_add_f32_e32 v59, v59, v60
	v_div_scale_f32 v60, s[68:69], v59, v59, v2
	v_rcp_f32_e32 v61, v60
	v_div_scale_f32 v62, vcc, v2, v59, v2
	v_fma_f32 v63, -v60, v61, 1.0
	v_fmac_f32_e32 v61, v63, v61
	v_mul_f32_e32 v63, v62, v61
	v_fma_f32 v64, -v60, v63, v62
	v_fmac_f32_e32 v63, v64, v61
	v_fma_f32 v60, -v60, v63, v62
	v_div_fmas_f32 v60, v60, v61, v63
	v_div_fixup_f32 v2, v60, v59, v2
	s_waitcnt lgkmcnt(0)
	ds_write2_b32 v28, v3, v2 offset0:16 offset1:144
	s_branch .LBB0_921
